# attention fast path: skip the attempt when the row reference is still the -1e30 initial value (first computed tile of a unit goes straight to the original body); on top of v058
# speedup vs baseline: 1.0007x; 1.0007x over previous
.LBB0_873:
	s_cmpk_eq_i32 s71, 0xffd0
	s_cselect_b64 s[34:35], -1, 0
	s_and_b64 s[4:5], s[34:35], exec
	s_cselect_b32 s84, 0, s71
	s_cmp_gt_i32 s84, s29
	s_cselect_b64 s[4:5], -1, 0
	s_or_b64 s[4:5], s[58:59], s[4:5]
	s_and_b64 vcc, exec, s[4:5]
	s_cbranch_vccnz .LBB0_883
	s_add_i32 s4, s84, 63
	s_cmp_gt_i32 s4, s95
	s_cselect_b64 s[4:5], -1, 0
	s_or_b64 s[4:5], s[34:35], s[4:5]
	s_and_b64 vcc, exec, s[4:5]
	s_cbranch_vccnz .Lattn_orig
	v_cmp_gt_f32_e32 vcc, 0xf0a18f08, v227
	s_cbranch_vccnz .Lattn_orig
	ds_read_b128 v[88:91], v221
	ds_read_b128 v[92:95], v221 offset:64
	ds_read_b128 v[164:167], v221 offset:576
	ds_read_b128 v[168:171], v221 offset:640
	ds_read_b128 v[172:175], v221 offset:4608
	ds_read_b128 v[236:239], v221 offset:4672
	ds_read_b128 v[240:243], v221 offset:5184
	ds_read_b128 v[160:163], v221 offset:5248
	v_readlane_b32 s4, v84, 0
	v_readlane_b32 s5, v75, 63
	v_pk_add_f32 v[116:117], v[140:141], v[84:85] neg_lo:[0,1] neg_hi:[0,1]
	v_pk_add_f32 v[118:119], v[140:141], v[86:87] neg_lo:[0,1] neg_hi:[0,1]
	v_pk_add_f32 v[100:101], v[142:143], v[84:85] neg_lo:[0,1] neg_hi:[0,1]
	v_pk_add_f32 v[102:103], v[142:143], v[86:87] neg_lo:[0,1] neg_hi:[0,1]
	v_pk_add_f32 v[112:113], v[140:141], v[76:77] neg_lo:[0,1] neg_hi:[0,1]
	v_pk_add_f32 v[114:115], v[140:141], v[78:79] neg_lo:[0,1] neg_hi:[0,1]
	v_pk_add_f32 v[96:97], v[142:143], v[76:77] neg_lo:[0,1] neg_hi:[0,1]
	v_pk_add_f32 v[98:99], v[142:143], v[78:79] neg_lo:[0,1] neg_hi:[0,1]
	v_pk_add_f32 v[108:109], v[140:141], v[80:81] neg_lo:[0,1] neg_hi:[0,1]
	v_pk_add_f32 v[110:111], v[140:141], v[82:83] neg_lo:[0,1] neg_hi:[0,1]
	v_pk_add_f32 v[244:245], v[142:143], v[80:81] neg_lo:[0,1] neg_hi:[0,1]
	v_pk_add_f32 v[246:247], v[142:143], v[82:83] neg_lo:[0,1] neg_hi:[0,1]
	v_pk_add_f32 v[104:105], v[140:141], v[72:73] neg_lo:[0,1] neg_hi:[0,1]
	v_pk_add_f32 v[106:107], v[140:141], v[74:75] neg_lo:[0,1] neg_hi:[0,1]
	v_pk_add_f32 v[248:249], v[142:143], v[72:73] neg_lo:[0,1] neg_hi:[0,1]
	v_pk_add_f32 v[250:251], v[142:143], v[74:75] neg_lo:[0,1] neg_hi:[0,1]
	v_mov_b32_e32 v234, s5
	v_sub_f32_e32 v234, s4, v234
	v_add_f32_e32 v231, v227, v234
	v_add_f32_e32 v230, v226, v234
	v_exp_f32_e64 v232, -v234
	v_pk_add_f32 v[116:117], v[116:117], v[230:231] op_sel:[0,1] op_sel_hi:[1,1] neg_lo:[0,1] neg_hi:[0,1]
	v_pk_add_f32 v[118:119], v[118:119], v[230:231] op_sel:[0,1] op_sel_hi:[1,1] neg_lo:[0,1] neg_hi:[0,1]
	v_pk_add_f32 v[100:101], v[100:101], v[230:231] op_sel_hi:[1,0] neg_lo:[0,1] neg_hi:[0,1]
	v_pk_add_f32 v[102:103], v[102:103], v[230:231] op_sel_hi:[1,0] neg_lo:[0,1] neg_hi:[0,1]
	v_pk_add_f32 v[112:113], v[112:113], v[230:231] op_sel:[0,1] op_sel_hi:[1,1] neg_lo:[0,1] neg_hi:[0,1]
	v_pk_add_f32 v[114:115], v[114:115], v[230:231] op_sel:[0,1] op_sel_hi:[1,1] neg_lo:[0,1] neg_hi:[0,1]
	v_pk_add_f32 v[96:97], v[96:97], v[230:231] op_sel_hi:[1,0] neg_lo:[0,1] neg_hi:[0,1]
	v_pk_add_f32 v[98:99], v[98:99], v[230:231] op_sel_hi:[1,0] neg_lo:[0,1] neg_hi:[0,1]
	v_pk_add_f32 v[108:109], v[108:109], v[230:231] op_sel:[0,1] op_sel_hi:[1,1] neg_lo:[0,1] neg_hi:[0,1]
	v_pk_add_f32 v[110:111], v[110:111], v[230:231] op_sel:[0,1] op_sel_hi:[1,1] neg_lo:[0,1] neg_hi:[0,1]
	v_pk_add_f32 v[244:245], v[244:245], v[230:231] op_sel_hi:[1,0] neg_lo:[0,1] neg_hi:[0,1]
	v_pk_add_f32 v[246:247], v[246:247], v[230:231] op_sel_hi:[1,0] neg_lo:[0,1] neg_hi:[0,1]
	v_pk_add_f32 v[104:105], v[104:105], v[230:231] op_sel:[0,1] op_sel_hi:[1,1] neg_lo:[0,1] neg_hi:[0,1]
	v_pk_add_f32 v[106:107], v[106:107], v[230:231] op_sel:[0,1] op_sel_hi:[1,1] neg_lo:[0,1] neg_hi:[0,1]
	v_pk_add_f32 v[248:249], v[248:249], v[230:231] op_sel_hi:[1,0] neg_lo:[0,1] neg_hi:[0,1]
	v_pk_add_f32 v[250:251], v[250:251], v[230:231] op_sel_hi:[1,0] neg_lo:[0,1] neg_hi:[0,1]
	s_waitcnt lgkmcnt(4)
	v_mfma_f32_16x16x32_bf16 v[116:119], v[88:91], v[0:3], v[116:119]
	v_mfma_f32_16x16x32_bf16 v[100:103], v[88:91], v[8:11], v[100:103]
	v_mfma_f32_16x16x32_bf16 v[112:115], v[164:167], v[0:3], v[112:115]
	v_mfma_f32_16x16x32_bf16 v[96:99], v[164:167], v[8:11], v[96:99]
	v_mfma_f32_16x16x32_bf16 v[116:119], v[92:95], v[4:7], v[116:119]
	v_mfma_f32_16x16x32_bf16 v[100:103], v[92:95], v[12:15], v[100:103]
	v_mfma_f32_16x16x32_bf16 v[112:115], v[168:171], v[4:7], v[112:115]
	v_mfma_f32_16x16x32_bf16 v[96:99], v[168:171], v[12:15], v[96:99]
	s_waitcnt lgkmcnt(0)
	v_mfma_f32_16x16x32_bf16 v[108:111], v[172:175], v[0:3], v[108:111]
	v_mfma_f32_16x16x32_bf16 v[244:247], v[172:175], v[8:11], v[244:247]
	v_mfma_f32_16x16x32_bf16 v[104:107], v[240:243], v[0:3], v[104:107]
	v_mfma_f32_16x16x32_bf16 v[248:251], v[240:243], v[8:11], v[248:251]
	v_mfma_f32_16x16x32_bf16 v[108:111], v[236:239], v[4:7], v[108:111]
	v_mfma_f32_16x16x32_bf16 v[244:247], v[236:239], v[12:15], v[244:247]
	v_mfma_f32_16x16x32_bf16 v[104:107], v[160:163], v[4:7], v[104:107]
	v_mfma_f32_16x16x32_bf16 v[248:251], v[160:163], v[12:15], v[248:251]
	ds_read_b128 v[88:91], v222 offset:9216
	ds_read_b128 v[92:95], v222 offset:9280
	ds_read_b128 v[164:167], v222 offset:11520
	ds_read_b128 v[168:171], v222 offset:11584
	ds_read_b128 v[172:175], v222 offset:13824
	ds_read_b128 v[236:239], v222 offset:13888
	ds_read_b128 v[240:243], v223 offset:9216
	ds_read_b128 v[160:163], v223 offset:9280
	v_max3_f32 v228, v116, v117, v118
	v_max3_f32 v229, v100, v101, v102
	v_max3_f32 v228, v228, v119, v112
	v_max3_f32 v229, v229, v103, v96
	v_max3_f32 v228, v228, v113, v114
	v_max3_f32 v229, v229, v97, v98
	v_max3_f32 v228, v228, v115, v108
	v_max3_f32 v229, v229, v99, v244
	v_max3_f32 v228, v228, v109, v110
	v_max3_f32 v229, v229, v245, v246
	v_max3_f32 v228, v228, v111, v104
	v_max3_f32 v229, v229, v247, v248
	v_max3_f32 v228, v228, v105, v106
	v_max3_f32 v229, v229, v249, v250
	v_max_f32_e32 v228, v228, v107
	v_max_f32_e32 v229, v229, v251
	v_max_f32_e32 v202, v228, v229
	v_cmp_lt_f32_e32 vcc, 0x42800000, v202
	s_cbranch_vccnz .Lattn_orig
	v_mov_b32_e32 v226, v230
	v_mov_b32_e32 v227, v231
	v_pk_mul_f32 v[52:53], v[52:53], v[232:233] op_sel_hi:[1,0]
	v_pk_mul_f32 v[54:55], v[54:55], v[232:233] op_sel_hi:[1,0]
	v_pk_mul_f32 v[44:45], v[44:45], v[232:233] op_sel_hi:[1,0]
	v_pk_mul_f32 v[46:47], v[46:47], v[232:233] op_sel_hi:[1,0]
	v_pk_mul_f32 v[40:41], v[40:41], v[232:233] op_sel_hi:[1,0]
	v_pk_mul_f32 v[42:43], v[42:43], v[232:233] op_sel_hi:[1,0]
	v_pk_mul_f32 v[48:49], v[48:49], v[232:233] op_sel_hi:[1,0]
	v_pk_mul_f32 v[50:51], v[50:51], v[232:233] op_sel_hi:[1,0]
	v_pk_mul_f32 v[36:37], v[36:37], v[232:233] op_sel_hi:[1,0]
	v_pk_mul_f32 v[38:39], v[38:39], v[232:233] op_sel_hi:[1,0]
	v_pk_mul_f32 v[28:29], v[28:29], v[232:233] op_sel_hi:[1,0]
	v_pk_mul_f32 v[30:31], v[30:31], v[232:233] op_sel_hi:[1,0]
	v_pk_mul_f32 v[16:17], v[16:17], v[232:233] op_sel_hi:[1,0]
	v_pk_mul_f32 v[18:19], v[18:19], v[232:233] op_sel_hi:[1,0]
	v_pk_mul_f32 v[32:33], v[32:33], v[232:233] op_sel_hi:[1,0]
	v_pk_mul_f32 v[34:35], v[34:35], v[232:233] op_sel_hi:[1,0]
	v_exp_f32_e32 v116, v116
	v_exp_f32_e32 v117, v117
	v_exp_f32_e32 v118, v118
	v_exp_f32_e32 v119, v119
	v_exp_f32_e32 v112, v112
	v_exp_f32_e32 v113, v113
	v_exp_f32_e32 v114, v114
	v_exp_f32_e32 v115, v115
	v_exp_f32_e32 v108, v108
	v_exp_f32_e32 v109, v109
	v_exp_f32_e32 v110, v110
	v_exp_f32_e32 v111, v111
	v_exp_f32_e32 v104, v104
	v_exp_f32_e32 v105, v105
	v_exp_f32_e32 v106, v106
	v_exp_f32_e32 v107, v107
	v_exp_f32_e32 v100, v100
	v_exp_f32_e32 v101, v101
	v_exp_f32_e32 v102, v102
	v_exp_f32_e32 v103, v103
	v_exp_f32_e32 v96, v96
	v_exp_f32_e32 v97, v97
	v_exp_f32_e32 v98, v98
	v_exp_f32_e32 v99, v99
	v_exp_f32_e32 v244, v244
	v_exp_f32_e32 v245, v245
	v_exp_f32_e32 v246, v246
	v_exp_f32_e32 v247, v247
	v_exp_f32_e32 v248, v248
	v_exp_f32_e32 v249, v249
	v_exp_f32_e32 v250, v250
	v_exp_f32_e32 v251, v251
	v_add_f32_e32 v228, 0, v116
	v_add_f32_e32 v229, 0, v100
	v_add_f32_e32 v228, v117, v228
	v_add_f32_e32 v229, v101, v229
	v_add_f32_e32 v228, v118, v228
	v_add_f32_e32 v229, v102, v229
	v_add_f32_e32 v228, v119, v228
	v_add_f32_e32 v229, v103, v229
	v_add_f32_e32 v228, v112, v228
	v_add_f32_e32 v229, v96, v229
	v_add_f32_e32 v228, v113, v228
	v_add_f32_e32 v229, v97, v229
	v_add_f32_e32 v228, v114, v228
	v_add_f32_e32 v229, v98, v229
	v_add_f32_e32 v228, v115, v228
	v_add_f32_e32 v229, v99, v229
	v_add_f32_e32 v228, v108, v228
	v_add_f32_e32 v229, v244, v229
	v_add_f32_e32 v228, v109, v228
	v_add_f32_e32 v229, v245, v229
	v_add_f32_e32 v228, v110, v228
	v_add_f32_e32 v229, v246, v229
	v_add_f32_e32 v228, v111, v228
	v_add_f32_e32 v229, v247, v229
	v_add_f32_e32 v228, v104, v228
	v_add_f32_e32 v229, v248, v229
	v_add_f32_e32 v228, v105, v228
	v_add_f32_e32 v229, v249, v229
	v_add_f32_e32 v228, v106, v228
	v_add_f32_e32 v229, v250, v229
	v_add_f32_e32 v228, v107, v228
	v_add_f32_e32 v229, v251, v229
	v_cvt_pk_bf16_f32 v76, v116, v117
	v_cvt_pk_bf16_f32 v77, v118, v119
	v_cvt_pk_bf16_f32 v78, v112, v113
	v_cvt_pk_bf16_f32 v79, v114, v115
	v_cvt_pk_bf16_f32 v84, v100, v101
	v_cvt_pk_bf16_f32 v85, v102, v103
	v_cvt_pk_bf16_f32 v86, v96, v97
	v_cvt_pk_bf16_f32 v87, v98, v99
	v_cvt_pk_bf16_f32 v72, v108, v109
	v_cvt_pk_bf16_f32 v73, v110, v111
	v_cvt_pk_bf16_f32 v74, v104, v105
	v_cvt_pk_bf16_f32 v75, v106, v107
	v_cvt_pk_bf16_f32 v80, v244, v245
	v_cvt_pk_bf16_f32 v81, v246, v247
	v_cvt_pk_bf16_f32 v82, v248, v249
	v_cvt_pk_bf16_f32 v83, v250, v251
	v_fma_f32 v225, v225, v232, v228
	v_fma_f32 v224, v224, v232, v229
	s_nop 1
	s_waitcnt lgkmcnt(7)
	v_mfma_f32_16x16x32_bf16 v[52:55], v[88:91], v[76:79], v[52:55]
	v_mfma_f32_16x16x32_bf16 v[36:39], v[88:91], v[84:87], v[36:39]
	s_waitcnt lgkmcnt(6)
	v_mfma_f32_16x16x32_bf16 v[52:55], v[92:95], v[72:75], v[52:55]
	v_mfma_f32_16x16x32_bf16 v[36:39], v[92:95], v[80:83], v[36:39]
	s_waitcnt lgkmcnt(5)
	v_mfma_f32_16x16x32_bf16 v[44:47], v[164:167], v[76:79], v[44:47]
	v_mfma_f32_16x16x32_bf16 v[28:31], v[164:167], v[84:87], v[28:31]
	s_waitcnt lgkmcnt(4)
	v_mfma_f32_16x16x32_bf16 v[44:47], v[168:171], v[72:75], v[44:47]
	v_mfma_f32_16x16x32_bf16 v[28:31], v[168:171], v[80:83], v[28:31]
	s_waitcnt lgkmcnt(3)
	v_mfma_f32_16x16x32_bf16 v[40:43], v[172:175], v[76:79], v[40:43]
	v_mfma_f32_16x16x32_bf16 v[16:19], v[172:175], v[84:87], v[16:19]
	s_waitcnt lgkmcnt(2)
	v_mfma_f32_16x16x32_bf16 v[40:43], v[236:239], v[72:75], v[40:43]
	v_mfma_f32_16x16x32_bf16 v[16:19], v[236:239], v[80:83], v[16:19]
	s_waitcnt lgkmcnt(1)
	v_mfma_f32_16x16x32_bf16 v[48:51], v[240:243], v[76:79], v[48:51]
	v_mfma_f32_16x16x32_bf16 v[32:35], v[240:243], v[84:87], v[32:35]
	s_waitcnt lgkmcnt(0)
	v_mfma_f32_16x16x32_bf16 v[48:51], v[160:163], v[72:75], v[48:51]
	v_mfma_f32_16x16x32_bf16 v[32:35], v[160:163], v[80:83], v[32:35]
	s_branch .LBB0_883
